# ml1 (mLSTM chunk-state) f32 outer-product accumulation moved from packed-f32 VALU FMAs to v_mfma_f32_32x32x2_f32 (exact f32), one 32x32 tile of both directions per wave
# speedup vs baseline: 1.0139x; 1.0139x over previous
; DI void ml1_item(const Params& p, int item, char* smem) {
;     ...
;     const int e = tid & 63, vq = tid >> 6;
;     float af[16], ab[16], nf = 0.f, nb = 0.f;
; #pragma unroll
;     for (int i = 0; i < 16; ++i) { af[i] = 0.f; ab[i] = 0.f; }
; #pragma unroll 2
;     for (int t = 0; t < 64; ++t) {
;         const float kk = sk[t * 64 + e], kf = kk * swt[t], kb = kk * swt[64 + t];
;         nf += kf; nb += kb;
; #pragma unroll
;         for (int i4 = 0; i4 < 4; ++i4) {
;             const float4 vv = *(const float4*)(sv + t * 64 + vq * 16 + 4 * i4);
;             af[4 * i4] += vv.x * kf; af[4 * i4 + 1] += vv.y * kf; af[4 * i4 + 2] += vv.z * kf; af[4 * i4 + 3] += vv.w * kf;
;             ab[4 * i4] += vv.x * kb; ab[4 * i4 + 1] += vv.y * kb; ab[4 * i4 + 2] += vv.z * kb; ab[4 * i4 + 3] += vv.w * kb;
;         }
;     }
.LBB0_234:
	s_or_b64 exec, exec, s[0:1]
	v_and_b32_e32 v61, 31, v34
	v_bfe_u32 v62, v34, 5, 1
	v_bfe_u32 v60, v34, 7, 1
	v_bfe_u32 v39, v34, 6, 1
	v_lshl_add_u32 v36, v62, 6, v61
	v_lshl_add_u32 v37, v39, 5, v36
	v_lshl_add_u32 v36, v60, 5, v36
	v_lshl_add_u32 v36, v36, 2, s12
	v_lshl_add_u32 v37, v37, 2, s25
	v_lshl_add_u32 v38, v62, 2, s11
	v_lshlrev_b32_e32 v60, 5, v60
	v_lshl_add_u32 v60, v62, 2, v60
	v_lshl_add_u32 v61, v39, 5, v61
	v_lshl_add_u32 v39, v60, 6, v61
	v_lshlrev_b32_e32 v39, 1, v39
	v_or_b32_e32 v60, 0x1000, v61
	v_lshlrev_b32_e32 v60, 1, v60
	v_mov_b32_e32 v32, 0
	v_mov_b32_e32 v33, 0
	s_mov_b32 s42, 0x800000
	s_waitcnt lgkmcnt(0)
	s_barrier
	ds_read_b32 v40, v36
	ds_read_b32 v41, v37
	ds_read2_b32 v[42:43], v38 offset0:0 offset1:64
	ds_read_b32 v44, v36 offset:512
	ds_read_b32 v45, v37 offset:512
	ds_read2_b32 v[46:47], v38 offset0:2 offset1:66
	ds_read_b32 v48, v36 offset:1024
	ds_read_b32 v49, v37 offset:1024
	ds_read2_b32 v[50:51], v38 offset0:4 offset1:68
	ds_read_b32 v52, v36 offset:1536
	ds_read_b32 v53, v37 offset:1536
	ds_read2_b32 v[54:55], v38 offset0:6 offset1:70
	s_waitcnt lgkmcnt(9)
	v_mul_f32_e32 v56, v41, v42
	v_mul_f32_e32 v57, v41, v43
	v_add_f32_e32 v32, v32, v56
	v_mfma_f32_32x32x2_f32 v[0:15], v40, v56, 0
	v_add_f32_e32 v33, v33, v57
	v_mfma_f32_32x32x2_f32 v[16:31], v40, v57, 0
	ds_read_b32 v40, v36 offset:2048
	ds_read_b32 v41, v37 offset:2048
	ds_read2_b32 v[42:43], v38 offset0:8 offset1:72
	s_waitcnt lgkmcnt(9)
	v_mul_f32_e32 v58, v45, v46
	v_mul_f32_e32 v59, v45, v47
	v_add_f32_e32 v32, v32, v58
	v_mfma_f32_32x32x2_f32 v[0:15], v44, v58, v[0:15]
	v_add_f32_e32 v33, v33, v59
	v_mfma_f32_32x32x2_f32 v[16:31], v44, v59, v[16:31]
	ds_read_b32 v44, v36 offset:2560
	ds_read_b32 v45, v37 offset:2560
	ds_read2_b32 v[46:47], v38 offset0:10 offset1:74
	s_waitcnt lgkmcnt(9)
	v_mul_f32_e32 v56, v49, v50
	v_mul_f32_e32 v57, v49, v51
	v_add_f32_e32 v32, v32, v56
	v_mfma_f32_32x32x2_f32 v[0:15], v48, v56, v[0:15]
	v_add_f32_e32 v33, v33, v57
	v_mfma_f32_32x32x2_f32 v[16:31], v48, v57, v[16:31]
	ds_read_b32 v48, v36 offset:3072
	ds_read_b32 v49, v37 offset:3072
	ds_read2_b32 v[50:51], v38 offset0:12 offset1:76
	s_waitcnt lgkmcnt(9)
	v_mul_f32_e32 v58, v53, v54
	v_mul_f32_e32 v59, v53, v55
	v_add_f32_e32 v32, v32, v58
	v_mfma_f32_32x32x2_f32 v[0:15], v52, v58, v[0:15]
	v_add_f32_e32 v33, v33, v59
	v_mfma_f32_32x32x2_f32 v[16:31], v52, v59, v[16:31]
	ds_read_b32 v52, v36 offset:3584
	ds_read_b32 v53, v37 offset:3584
	ds_read2_b32 v[54:55], v38 offset0:14 offset1:78
	s_waitcnt lgkmcnt(9)
	v_mul_f32_e32 v56, v41, v42
	v_mul_f32_e32 v57, v41, v43
	v_add_f32_e32 v32, v32, v56
	v_mfma_f32_32x32x2_f32 v[0:15], v40, v56, v[0:15]
	v_add_f32_e32 v33, v33, v57
	v_mfma_f32_32x32x2_f32 v[16:31], v40, v57, v[16:31]
	ds_read_b32 v40, v36 offset:4096
	ds_read_b32 v41, v37 offset:4096
	ds_read2_b32 v[42:43], v38 offset0:16 offset1:80
	s_waitcnt lgkmcnt(9)
	v_mul_f32_e32 v58, v45, v46
	v_mul_f32_e32 v59, v45, v47
	v_add_f32_e32 v32, v32, v58
	v_mfma_f32_32x32x2_f32 v[0:15], v44, v58, v[0:15]
	v_add_f32_e32 v33, v33, v59
	v_mfma_f32_32x32x2_f32 v[16:31], v44, v59, v[16:31]
	ds_read_b32 v44, v36 offset:4608
	ds_read_b32 v45, v37 offset:4608
	ds_read2_b32 v[46:47], v38 offset0:18 offset1:82
	s_waitcnt lgkmcnt(9)
	v_mul_f32_e32 v56, v49, v50
	v_mul_f32_e32 v57, v49, v51
	v_add_f32_e32 v32, v32, v56
	v_mfma_f32_32x32x2_f32 v[0:15], v48, v56, v[0:15]
	v_add_f32_e32 v33, v33, v57
	v_mfma_f32_32x32x2_f32 v[16:31], v48, v57, v[16:31]
	ds_read_b32 v48, v36 offset:5120
	ds_read_b32 v49, v37 offset:5120
	ds_read2_b32 v[50:51], v38 offset0:20 offset1:84
	s_waitcnt lgkmcnt(9)
	v_mul_f32_e32 v58, v53, v54
	v_mul_f32_e32 v59, v53, v55
	v_add_f32_e32 v32, v32, v58
	v_mfma_f32_32x32x2_f32 v[0:15], v52, v58, v[0:15]
	v_add_f32_e32 v33, v33, v59
	v_mfma_f32_32x32x2_f32 v[16:31], v52, v59, v[16:31]
	ds_read_b32 v52, v36 offset:5632
	ds_read_b32 v53, v37 offset:5632
	ds_read2_b32 v[54:55], v38 offset0:22 offset1:86
	s_waitcnt lgkmcnt(9)
	v_mul_f32_e32 v56, v41, v42
	v_mul_f32_e32 v57, v41, v43
	v_add_f32_e32 v32, v32, v56
	v_mfma_f32_32x32x2_f32 v[0:15], v40, v56, v[0:15]
	v_add_f32_e32 v33, v33, v57
	v_mfma_f32_32x32x2_f32 v[16:31], v40, v57, v[16:31]
	ds_read_b32 v40, v36 offset:6144
	ds_read_b32 v41, v37 offset:6144
	ds_read2_b32 v[42:43], v38 offset0:24 offset1:88
	s_waitcnt lgkmcnt(9)
	v_mul_f32_e32 v58, v45, v46
	v_mul_f32_e32 v59, v45, v47
	v_add_f32_e32 v32, v32, v58
	v_mfma_f32_32x32x2_f32 v[0:15], v44, v58, v[0:15]
	v_add_f32_e32 v33, v33, v59
	v_mfma_f32_32x32x2_f32 v[16:31], v44, v59, v[16:31]
	ds_read_b32 v44, v36 offset:6656
	ds_read_b32 v45, v37 offset:6656
	ds_read2_b32 v[46:47], v38 offset0:26 offset1:90
	s_waitcnt lgkmcnt(9)
	v_mul_f32_e32 v56, v49, v50
	v_mul_f32_e32 v57, v49, v51
	v_add_f32_e32 v32, v32, v56
	v_mfma_f32_32x32x2_f32 v[0:15], v48, v56, v[0:15]
	v_add_f32_e32 v33, v33, v57
	v_mfma_f32_32x32x2_f32 v[16:31], v48, v57, v[16:31]
	ds_read_b32 v48, v36 offset:7168
	ds_read_b32 v49, v37 offset:7168
	ds_read2_b32 v[50:51], v38 offset0:28 offset1:92
	s_waitcnt lgkmcnt(9)
	v_mul_f32_e32 v58, v53, v54
	v_mul_f32_e32 v59, v53, v55
	v_add_f32_e32 v32, v32, v58
	v_mfma_f32_32x32x2_f32 v[0:15], v52, v58, v[0:15]
	v_add_f32_e32 v33, v33, v59
	v_mfma_f32_32x32x2_f32 v[16:31], v52, v59, v[16:31]
	ds_read_b32 v52, v36 offset:7680
	ds_read_b32 v53, v37 offset:7680
	ds_read2_b32 v[54:55], v38 offset0:30 offset1:94
	s_waitcnt lgkmcnt(9)
	v_mul_f32_e32 v56, v41, v42
	v_mul_f32_e32 v57, v41, v43
	v_add_f32_e32 v32, v32, v56
	v_mfma_f32_32x32x2_f32 v[0:15], v40, v56, v[0:15]
	v_add_f32_e32 v33, v33, v57
	v_mfma_f32_32x32x2_f32 v[16:31], v40, v57, v[16:31]
	ds_read_b32 v40, v36 offset:8192
	ds_read_b32 v41, v37 offset:8192
	ds_read2_b32 v[42:43], v38 offset0:32 offset1:96
	s_waitcnt lgkmcnt(9)
; DI void ml1_item(const Params& p, int item, char* smem) {
;     ...
;     for (int t = 0; t < 64; ++t) {
;         const float kk = sk[t * 64 + e], kf = kk * swt[t], kb = kk * swt[64 + t];
;         nf += kf; nb += kb;
; #pragma unroll
;         for (int i4 = 0; i4 < 4; ++i4) {
;             const float4 vv = *(const float4*)(sv + t * 64 + vq * 16 + 4 * i4);
;             af[4 * i4] += vv.x * kf; af[4 * i4 + 1] += vv.y * kf; af[4 * i4 + 2] += vv.z * kf; af[4 * i4 + 3] += vv.w * kf;
;             ab[4 * i4] += vv.x * kb; ab[4 * i4 + 1] += vv.y * kb; ab[4 * i4 + 2] += vv.z * kb; ab[4 * i4 + 3] += vv.w * kb;
;         }
;     }
	v_mul_f32_e32 v58, v45, v46
	v_mul_f32_e32 v59, v45, v47
	v_add_f32_e32 v32, v32, v58
	v_mfma_f32_32x32x2_f32 v[0:15], v44, v58, v[0:15]
	v_add_f32_e32 v33, v33, v59
	v_mfma_f32_32x32x2_f32 v[16:31], v44, v59, v[16:31]
	ds_read_b32 v44, v36 offset:8704
	ds_read_b32 v45, v37 offset:8704
	ds_read2_b32 v[46:47], v38 offset0:34 offset1:98
	s_waitcnt lgkmcnt(9)
	v_mul_f32_e32 v56, v49, v50
	v_mul_f32_e32 v57, v49, v51
	v_add_f32_e32 v32, v32, v56
	v_mfma_f32_32x32x2_f32 v[0:15], v48, v56, v[0:15]
	v_add_f32_e32 v33, v33, v57
	v_mfma_f32_32x32x2_f32 v[16:31], v48, v57, v[16:31]
	ds_read_b32 v48, v36 offset:9216
	ds_read_b32 v49, v37 offset:9216
	ds_read2_b32 v[50:51], v38 offset0:36 offset1:100
	s_waitcnt lgkmcnt(9)
	v_mul_f32_e32 v58, v53, v54
	v_mul_f32_e32 v59, v53, v55
	v_add_f32_e32 v32, v32, v58
	v_mfma_f32_32x32x2_f32 v[0:15], v52, v58, v[0:15]
	v_add_f32_e32 v33, v33, v59
	v_mfma_f32_32x32x2_f32 v[16:31], v52, v59, v[16:31]
	ds_read_b32 v52, v36 offset:9728
	ds_read_b32 v53, v37 offset:9728
	ds_read2_b32 v[54:55], v38 offset0:38 offset1:102
	s_waitcnt lgkmcnt(9)
	v_mul_f32_e32 v56, v41, v42
	v_mul_f32_e32 v57, v41, v43
	v_add_f32_e32 v32, v32, v56
	v_mfma_f32_32x32x2_f32 v[0:15], v40, v56, v[0:15]
	v_add_f32_e32 v33, v33, v57
	v_mfma_f32_32x32x2_f32 v[16:31], v40, v57, v[16:31]
	ds_read_b32 v40, v36 offset:10240
	ds_read_b32 v41, v37 offset:10240
	ds_read2_b32 v[42:43], v38 offset0:40 offset1:104
	s_waitcnt lgkmcnt(9)
	v_mul_f32_e32 v58, v45, v46
	v_mul_f32_e32 v59, v45, v47
	v_add_f32_e32 v32, v32, v58
	v_mfma_f32_32x32x2_f32 v[0:15], v44, v58, v[0:15]
	v_add_f32_e32 v33, v33, v59
	v_mfma_f32_32x32x2_f32 v[16:31], v44, v59, v[16:31]
	ds_read_b32 v44, v36 offset:10752
	ds_read_b32 v45, v37 offset:10752
	ds_read2_b32 v[46:47], v38 offset0:42 offset1:106
	s_waitcnt lgkmcnt(9)
	v_mul_f32_e32 v56, v49, v50
	v_mul_f32_e32 v57, v49, v51
	v_add_f32_e32 v32, v32, v56
	v_mfma_f32_32x32x2_f32 v[0:15], v48, v56, v[0:15]
	v_add_f32_e32 v33, v33, v57
	v_mfma_f32_32x32x2_f32 v[16:31], v48, v57, v[16:31]
	ds_read_b32 v48, v36 offset:11264
	ds_read_b32 v49, v37 offset:11264
	ds_read2_b32 v[50:51], v38 offset0:44 offset1:108
	s_waitcnt lgkmcnt(9)
	v_mul_f32_e32 v58, v53, v54
	v_mul_f32_e32 v59, v53, v55
	v_add_f32_e32 v32, v32, v58
	v_mfma_f32_32x32x2_f32 v[0:15], v52, v58, v[0:15]
	v_add_f32_e32 v33, v33, v59
	v_mfma_f32_32x32x2_f32 v[16:31], v52, v59, v[16:31]
	ds_read_b32 v52, v36 offset:11776
	ds_read_b32 v53, v37 offset:11776
	ds_read2_b32 v[54:55], v38 offset0:46 offset1:110
	s_waitcnt lgkmcnt(9)
	v_mul_f32_e32 v56, v41, v42
	v_mul_f32_e32 v57, v41, v43
	v_add_f32_e32 v32, v32, v56
	v_mfma_f32_32x32x2_f32 v[0:15], v40, v56, v[0:15]
	v_add_f32_e32 v33, v33, v57
	v_mfma_f32_32x32x2_f32 v[16:31], v40, v57, v[16:31]
	ds_read_b32 v40, v36 offset:12288
	ds_read_b32 v41, v37 offset:12288
	ds_read2_b32 v[42:43], v38 offset0:48 offset1:112
	s_waitcnt lgkmcnt(9)
	v_mul_f32_e32 v58, v45, v46
	v_mul_f32_e32 v59, v45, v47
	v_add_f32_e32 v32, v32, v58
	v_mfma_f32_32x32x2_f32 v[0:15], v44, v58, v[0:15]
	v_add_f32_e32 v33, v33, v59
	v_mfma_f32_32x32x2_f32 v[16:31], v44, v59, v[16:31]
	ds_read_b32 v44, v36 offset:12800
	ds_read_b32 v45, v37 offset:12800
	ds_read2_b32 v[46:47], v38 offset0:50 offset1:114
	s_waitcnt lgkmcnt(9)
	v_mul_f32_e32 v56, v49, v50
	v_mul_f32_e32 v57, v49, v51
	v_add_f32_e32 v32, v32, v56
	v_mfma_f32_32x32x2_f32 v[0:15], v48, v56, v[0:15]
	v_add_f32_e32 v33, v33, v57
	v_mfma_f32_32x32x2_f32 v[16:31], v48, v57, v[16:31]
	ds_read_b32 v48, v36 offset:13312
	ds_read_b32 v49, v37 offset:13312
	ds_read2_b32 v[50:51], v38 offset0:52 offset1:116
	s_waitcnt lgkmcnt(9)
	v_mul_f32_e32 v58, v53, v54
	v_mul_f32_e32 v59, v53, v55
	v_add_f32_e32 v32, v32, v58
	v_mfma_f32_32x32x2_f32 v[0:15], v52, v58, v[0:15]
	v_add_f32_e32 v33, v33, v59
	v_mfma_f32_32x32x2_f32 v[16:31], v52, v59, v[16:31]
	ds_read_b32 v52, v36 offset:13824
	ds_read_b32 v53, v37 offset:13824
	ds_read2_b32 v[54:55], v38 offset0:54 offset1:118
	s_waitcnt lgkmcnt(9)
	v_mul_f32_e32 v56, v41, v42
	v_mul_f32_e32 v57, v41, v43
	v_add_f32_e32 v32, v32, v56
	v_mfma_f32_32x32x2_f32 v[0:15], v40, v56, v[0:15]
	v_add_f32_e32 v33, v33, v57
	v_mfma_f32_32x32x2_f32 v[16:31], v40, v57, v[16:31]
	ds_read_b32 v40, v36 offset:14336
	ds_read_b32 v41, v37 offset:14336
	ds_read2_b32 v[42:43], v38 offset0:56 offset1:120
	s_waitcnt lgkmcnt(9)
	v_mul_f32_e32 v58, v45, v46
	v_mul_f32_e32 v59, v45, v47
	v_add_f32_e32 v32, v32, v58
	v_mfma_f32_32x32x2_f32 v[0:15], v44, v58, v[0:15]
	v_add_f32_e32 v33, v33, v59
	v_mfma_f32_32x32x2_f32 v[16:31], v44, v59, v[16:31]
	ds_read_b32 v44, v36 offset:14848
	ds_read_b32 v45, v37 offset:14848
	ds_read2_b32 v[46:47], v38 offset0:58 offset1:122
	s_waitcnt lgkmcnt(9)
; DI bf16_t to_bf16(float a) { return (bf16_t)(pk_bf16(a, 0.f) & 0xffffu); }
; DI void ml1_item(const Params& p, int item, char* smem) {
;     ...
;     for (int t = 0; t < 64; ++t) {
;         const float kk = sk[t * 64 + e], kf = kk * swt[t], kb = kk * swt[64 + t];
;         nf += kf; nb += kb;
; #pragma unroll
;         for (int i4 = 0; i4 < 4; ++i4) {
;             const float4 vv = *(const float4*)(sv + t * 64 + vq * 16 + 4 * i4);
;             af[4 * i4] += vv.x * kf; af[4 * i4 + 1] += vv.y * kf; af[4 * i4 + 2] += vv.z * kf; af[4 * i4 + 3] += vv.w * kf;
;             ab[4 * i4] += vv.x * kb; ab[4 * i4 + 1] += vv.y * kb; ab[4 * i4 + 2] += vv.z * kb; ab[4 * i4 + 3] += vv.w * kb;
;         }
;     }
;     const size_t chf = ((size_t)(b * 4 + head) * 2 + 0) * NCH + chain_pos(0, c), chb = ((size_t)(b * 4 + head) * 2 + 1) * NCH + chain_pos(1, c);
;     bf16_t* df = p.ST + chf * STSZ; bf16_t* db = p.ST + chb * STSZ;
; #pragma unroll
;     for (int i = 0; i < 16; ++i) { df[(vq * 16 + i) * 64 + e] = to_bf16(af[i]); db[(vq * 16 + i) * 64 + e] = to_bf16(ab[i]); }
;     if (vq == 0) { df[4096 + e] = to_bf16(nf); db[4096 + e] = to_bf16(nb); }
;     if (tid == 0) { p.DEC[chf] = __expf(sg[63]); p.DEC[chb] = __expf(sg[128]); }
	v_mul_f32_e32 v56, v49, v50
	v_mul_f32_e32 v57, v49, v51
	v_add_f32_e32 v32, v32, v56
	v_mfma_f32_32x32x2_f32 v[0:15], v48, v56, v[0:15]
	v_add_f32_e32 v33, v33, v57
	v_mfma_f32_32x32x2_f32 v[16:31], v48, v57, v[16:31]
	ds_read_b32 v48, v36 offset:15360
	ds_read_b32 v49, v37 offset:15360
	ds_read2_b32 v[50:51], v38 offset0:60 offset1:124
	s_waitcnt lgkmcnt(9)
	v_mul_f32_e32 v58, v53, v54
	v_mul_f32_e32 v59, v53, v55
	v_add_f32_e32 v32, v32, v58
	v_mfma_f32_32x32x2_f32 v[0:15], v52, v58, v[0:15]
	v_add_f32_e32 v33, v33, v59
	v_mfma_f32_32x32x2_f32 v[16:31], v52, v59, v[16:31]
	ds_read_b32 v52, v36 offset:15872
	ds_read_b32 v53, v37 offset:15872
	ds_read2_b32 v[54:55], v38 offset0:62 offset1:126
	s_waitcnt lgkmcnt(9)
	v_mul_f32_e32 v56, v41, v42
	v_mul_f32_e32 v57, v41, v43
	v_add_f32_e32 v32, v32, v56
	v_mfma_f32_32x32x2_f32 v[0:15], v40, v56, v[0:15]
	v_add_f32_e32 v33, v33, v57
	v_mfma_f32_32x32x2_f32 v[16:31], v40, v57, v[16:31]
	s_waitcnt lgkmcnt(6)
	v_mul_f32_e32 v58, v45, v46
	v_mul_f32_e32 v59, v45, v47
	v_add_f32_e32 v32, v32, v58
	v_mfma_f32_32x32x2_f32 v[0:15], v44, v58, v[0:15]
	v_add_f32_e32 v33, v33, v59
	v_mfma_f32_32x32x2_f32 v[16:31], v44, v59, v[16:31]
	s_waitcnt lgkmcnt(3)
	v_mul_f32_e32 v56, v49, v50
	v_mul_f32_e32 v57, v49, v51
	v_add_f32_e32 v32, v32, v56
	v_mfma_f32_32x32x2_f32 v[0:15], v48, v56, v[0:15]
	v_add_f32_e32 v33, v33, v57
	v_mfma_f32_32x32x2_f32 v[16:31], v48, v57, v[16:31]
	s_waitcnt lgkmcnt(0)
	v_mul_f32_e32 v58, v53, v54
	v_mul_f32_e32 v59, v53, v55
	v_add_f32_e32 v32, v32, v58
	v_mfma_f32_32x32x2_f32 v[0:15], v52, v58, v[0:15]
	v_add_f32_e32 v33, v33, v59
	v_mfma_f32_32x32x2_f32 v[16:31], v52, v59, v[16:31]
	s_lshl_b32 s0, s6, 2
	s_or_b32 s0, s0, s7
	s_mul_i32 s19, s0, 0x108
	s_ashr_i32 s1, s17, 31
	s_mul_hi_i32 s18, s0, 0x108
	s_add_u32 s0, s19, s17
	s_addc_u32 s1, s18, s1
	s_and_b64 s[4:5], s[4:5], exec
	s_cselect_b32 s4, 3, 0x87
	s_sub_i32 s17, s4, s17
	s_add_u32 s4, s19, s17
	s_addc_u32 s5, s18, 0
	s_mulk_i32 s5, 0x2080
	s_mul_hi_u32 s6, s4, 0x2080
	s_add_i32 s6, s6, s5
	s_mul_i32 s7, s4, 0x2080
	s_mul_i32 s4, s1, 0x2080
	s_mul_hi_u32 s5, s0, 0x2080
	s_add_i32 s5, s5, s4
	s_mul_i32 s4, s0, 0x2080
	s_add_u32 s4, s68, s4
	s_addc_u32 s5, s69, s5
	s_add_u32 s7, s68, s7
	s_addc_u32 s8, s69, s6
	s_add_u32 s6, s7, 0x10c200
	s_addc_u32 s7, s8, 0
	v_mov_b32_e32 v61, v32
	s_nop 1
	v_permlane32_swap_b32_e32 v61, v32
	s_nop 0
	v_add_f32_e32 v32, v32, v61
	v_mov_b32_e32 v61, v33
	s_nop 1
	v_permlane32_swap_b32_e32 v61, v33
	s_nop 0
	v_add_f32_e32 v33, v33, v61
	v_cvt_pk_bf16_f32 v61, v0, v1
	global_store_short v39, v61, s[4:5]
	global_store_short_d16_hi v39, v61, s[4:5] offset:128
	v_cvt_pk_bf16_f32 v62, v2, v3
	global_store_short v39, v62, s[4:5] offset:256
	global_store_short_d16_hi v39, v62, s[4:5] offset:384
	v_cvt_pk_bf16_f32 v61, v4, v5
	global_store_short v39, v61, s[4:5] offset:1024
	global_store_short_d16_hi v39, v61, s[4:5] offset:1152
	v_cvt_pk_bf16_f32 v62, v6, v7
	global_store_short v39, v62, s[4:5] offset:1280
	global_store_short_d16_hi v39, v62, s[4:5] offset:1408
	v_cvt_pk_bf16_f32 v61, v8, v9
	global_store_short v39, v61, s[4:5] offset:2048
	global_store_short_d16_hi v39, v61, s[4:5] offset:2176
	v_cvt_pk_bf16_f32 v62, v10, v11
	global_store_short v39, v62, s[4:5] offset:2304
	global_store_short_d16_hi v39, v62, s[4:5] offset:2432
	v_cvt_pk_bf16_f32 v61, v12, v13
	global_store_short v39, v61, s[4:5] offset:3072
	global_store_short_d16_hi v39, v61, s[4:5] offset:3200
	v_cvt_pk_bf16_f32 v62, v14, v15
	global_store_short v39, v62, s[4:5] offset:3328
	global_store_short_d16_hi v39, v62, s[4:5] offset:3456
	v_cvt_pk_bf16_f32 v61, v16, v17
	global_store_short v39, v61, s[6:7]
	global_store_short_d16_hi v39, v61, s[6:7] offset:128
	v_cvt_pk_bf16_f32 v62, v18, v19
	global_store_short v39, v62, s[6:7] offset:256
	global_store_short_d16_hi v39, v62, s[6:7] offset:384
	v_cvt_pk_bf16_f32 v61, v20, v21
	global_store_short v39, v61, s[6:7] offset:1024
	global_store_short_d16_hi v39, v61, s[6:7] offset:1152
	v_cvt_pk_bf16_f32 v62, v22, v23
	global_store_short v39, v62, s[6:7] offset:1280
	global_store_short_d16_hi v39, v62, s[6:7] offset:1408
	v_cvt_pk_bf16_f32 v61, v24, v25
	global_store_short v39, v61, s[6:7] offset:2048
	global_store_short_d16_hi v39, v61, s[6:7] offset:2176
	v_cvt_pk_bf16_f32 v62, v26, v27
	global_store_short v39, v62, s[6:7] offset:2304
	global_store_short_d16_hi v39, v62, s[6:7] offset:2432
	v_cvt_pk_bf16_f32 v61, v28, v29
	global_store_short v39, v61, s[6:7] offset:3072
	global_store_short_d16_hi v39, v61, s[6:7] offset:3200
	v_cvt_pk_bf16_f32 v62, v30, v31
	global_store_short v39, v62, s[6:7] offset:3328
	global_store_short_d16_hi v39, v62, s[6:7] offset:3456
	v_and_b32_e32 v61, 0xa0, v34
	v_cmp_eq_u32_e32 vcc, 0, v61
	s_and_saveexec_b64 s[8:9], vcc
	s_cbranch_execz .LBB0_238
	v_cvt_pk_bf16_f32 v61, v32, v33
	global_store_short v60, v61, s[4:5]
	global_store_short_d16_hi v60, v61, s[6:7]
